# diff attention loop unrolled 2x with precomputed per-parity LDS addresses (removes seven VALU and six SALU address ops per iteration)
# speedup vs baseline: 1.0561x; 1.0017x over previous
; DI float shx(float v, int k) { return __int_as_float(__builtin_amdgcn_ds_bpermute((lane_id_l() ^ k) << 2, __float_as_int(v))); }
; DI int get_tid() { int t = threadIdx.x; asm volatile("" : "+v"(t)); return t; }
; DI void diff_attn_item(const Params& P, const WsPtrs& W, int layer, int item, unsigned char* smem) {
;   const int w = get_tid() >> 6, lane = get_tid() & 63, r = lane & 31, h = lane >> 5;
;   int bh = item >> 5, qb = item & 31, bl = bh >> 3, hh = bh & 7;
;   int sub = w >> 2;
;   int q0 = qb * 128 + 32 * (w & 3);
;   size_t tokb = (size_t)bl * 4096;
;   f32x16 o[4]; float l;
;   float gq = fabsf(P.in[I_DQG][layer * 64 + lane]), gk = fabsf(P.in[I_DKG][layer * 64 + lane]);
; #pragma unroll
;   for (int of = 32; of > 0; of >>= 1) { gq = fmaxf(gq, shx(gq, of)); gk = fmaxf(gk, shx(gk, of)); }
;   const float M = 11.5416f * gq * gk * 1.02f + 1.f;
;   if (M <= 56.f)
;     attn_core<128, 64, 1>(W.Y + (tokb + q0) * LDY + O_BQ + hh * 128 + sub * 64, LDY, W.Y + tokb * LDY + O_BK + hh * 128, LDY,
;                           W.BVT + (size_t)bh * 128 * 4096, sub * 64, q0, M, o, l, smem);
;   else
;     attn_core<128, 64, 0>(W.Y + (tokb + q0) * LDY + O_BQ + hh * 128 + sub * 64, LDY, W.Y + tokb * LDY + O_BK + hh * 128, LDY,
;                           W.BVT + (size_t)bh * 128 * 4096, sub * 64, q0, 0.f, o, l, smem);
.LBB0_558:
	v_readlane_b32 s2, v253, 10
	s_mov_b32 s8, s2
	v_mov_b32_e32 v161, v250
	s_waitcnt vmcnt(1)
	v_mov_b32_e32 v162, v250
	v_readlane_b32 s6, v255, 17
	v_and_b32_e32 v163, 63, v162
	v_readlane_b32 s20, v254, 49
	v_or_b32_e32 v0, s6, v163
	v_lshlrev_b64 v[2:3], 2, v[0:1]
	v_readlane_b32 s21, v254, 50
	v_readlane_b32 s22, v254, 51
	v_readlane_b32 s23, v254, 52
	v_lshl_add_u64 v[4:5], s[20:21], 0, v[2:3]
	global_load_dword v0, v[4:5], off
	v_lshl_add_u64 v[2:3], s[22:23], 0, v[2:3]
	global_load_dword v2, v[2:3], off
	v_mov_b32_e32 v3, v229
	v_mov_b32_e32 v4, v229
	v_mov_b32_e32 v5, v229
	v_lshlrev_b32_e32 v3, 2, v3
	v_lshlrev_b32_e32 v4, 2, v4
	v_xor_b32_e32 v3, 0x80, v3
	v_xor_b32_e32 v4, 0x80, v4
	v_mov_b32_e32 v6, v229
	v_mov_b32_e32 v7, v229
	v_lshlrev_b32_e32 v5, 2, v5
	v_lshlrev_b32_e32 v6, 2, v6
	v_xor_b32_e32 v5, 64, v5
	v_xor_b32_e32 v6, 64, v6
	v_mov_b32_e32 v8, v229
	v_mov_b32_e32 v9, v229
	v_lshlrev_b32_e32 v7, 2, v7
	v_lshlrev_b32_e32 v8, 2, v8
	v_xor_b32_e32 v7, 32, v7
	v_xor_b32_e32 v8, 32, v8
	v_mov_b32_e32 v10, v229
	v_mov_b32_e32 v11, v229
	v_lshlrev_b32_e32 v9, 2, v9
	v_lshlrev_b32_e32 v10, 2, v10
	v_xor_b32_e32 v9, 16, v9
	v_xor_b32_e32 v10, 16, v10
	v_mov_b32_e32 v12, v229
	v_mov_b32_e32 v13, v229
	v_lshlrev_b32_e32 v11, 2, v11
	v_lshlrev_b32_e32 v12, 2, v12
	v_xor_b32_e32 v11, 8, v11
	v_xor_b32_e32 v12, 8, v12
	v_mov_b32_e32 v14, v229
	s_ashr_i32 s9, s8, 31
	s_lshl_b64 s[10:11], s[8:9], 14
	v_lshlrev_b32_e32 v13, 2, v13
	s_add_u32 s22, s10, 0x7046100
	v_lshlrev_b32_e32 v14, 2, v14
	v_xor_b32_e32 v13, 4, v13
	s_addc_u32 s23, s11, 0
	v_xor_b32_e32 v14, 4, v14
	v_readlane_b32 s7, v255, 18
	s_add_u32 s12, s62, s22
	s_mul_i32 s21, s8, 0x6600000
	s_addc_u32 s13, s63, s23
	s_lshl_b64 s[6:7], s[8:9], 24
	s_mul_hi_i32 s20, s8, 0x6600000
	s_add_u32 s2, s12, s21
	v_readlane_b32 s26, v254, 55
	s_addc_u32 s14, s13, s20
	v_readlane_b32 s27, v254, 56
	s_add_u32 s26, s2, s6
	s_addc_u32 s27, s14, s7
	s_lshr_b32 s2, s19, 2
	s_bfe_i32 s14, s19, 0x180005
	s_lshl_b32 s6, s19, 7
	v_bfe_u32 v164, v161, 6, 2
	s_and_b32 s19, s2, 0x7fffff8
	s_ashr_i32 s15, s14, 31
	s_and_b32 s2, s6, 0xf80
	v_lshl_or_b32 v168, v164, 5, s2
	s_lshl_b64 s[6:7], s[14:15], 12
	s_mov_b32 s2, 0x3f828f5c
	v_readlane_b32 s24, v254, 53
	v_readlane_b32 s25, v254, 54
	v_ashrrev_i32_e32 v165, 8, v161
	s_waitcnt vmcnt(1)
	v_and_b32_e32 v15, 0x7fffffff, v0
	ds_bpermute_b32 v3, v3, v15
	s_waitcnt vmcnt(0)
	v_and_b32_e32 v16, 0x7fffffff, v2
	ds_bpermute_b32 v4, v4, v16
	v_max_f32_e64 v0, |v0|, |v0|
	v_max_f32_e64 v2, |v2|, |v2|
	s_waitcnt lgkmcnt(1)
	v_max_f32_e32 v3, v3, v3
	v_max_f32_e32 v0, v0, v3
	s_waitcnt lgkmcnt(0)
	v_max_f32_e32 v4, v4, v4
	v_max_f32_e32 v4, v2, v4
	ds_bpermute_b32 v5, v5, v0
	ds_bpermute_b32 v6, v6, v4
	v_mov_b64_e32 v[2:3], s[12:13]
	v_lshlrev_b32_e32 v146, 6, v165
	v_ashrrev_i32_e32 v147, 31, v146
	s_waitcnt lgkmcnt(1)
	v_max_f32_e32 v5, v5, v5
	s_waitcnt lgkmcnt(0)
	v_max_f32_e32 v6, v6, v6
	v_max_f32_e32 v0, v0, v5
	v_max_f32_e32 v4, v4, v6
	ds_bpermute_b32 v5, v7, v0
	ds_bpermute_b32 v6, v8, v4
	v_or_b32_e32 v7, s6, v168
	v_mad_u64_u32 v[2:3], s[24:25], v7, s33, v[2:3]
	s_waitcnt lgkmcnt(1)
	v_max_f32_e32 v5, v5, v5
	s_waitcnt lgkmcnt(0)
	v_max_f32_e32 v6, v6, v6
	v_max_f32_e32 v0, v0, v5
	v_max_f32_e32 v4, v4, v6
	ds_bpermute_b32 v5, v9, v0
	ds_bpermute_b32 v6, v10, v4
	s_or_b32 s16, s19, s81
	s_mov_b64 s[24:25], 0x1000
	s_bfe_i32 s16, s16, 0x1b0000
	s_waitcnt lgkmcnt(1)
	v_max_f32_e32 v5, v5, v5
	s_waitcnt lgkmcnt(0)
	v_max_f32_e32 v6, v6, v6
	v_max_f32_e32 v0, v0, v5
	v_max_f32_e32 v4, v4, v6
	ds_bpermute_b32 v5, v11, v0
	ds_bpermute_b32 v6, v12, v4
	s_waitcnt lgkmcnt(1)
	v_max_f32_e32 v5, v5, v5
	s_waitcnt lgkmcnt(0)
	v_max_f32_e32 v6, v6, v6
	v_max_f32_e32 v0, v0, v5
	v_max_f32_e32 v4, v4, v6
	ds_bpermute_b32 v5, v13, v0
	ds_bpermute_b32 v6, v14, v4
	s_waitcnt lgkmcnt(1)
	v_max_f32_e32 v5, v5, v5
	s_waitcnt lgkmcnt(0)
	v_max_f32_e32 v6, v6, v6
	v_max_f32_e32 v0, v0, v5
	v_max_f32_e32 v4, v4, v6
	v_mul_f32_e32 v0, 0x4138aa65, v0
	v_mul_f32_e32 v0, v0, v4
	v_fma_f32 v0, v0, s2, 1.0
	s_mov_b32 s2, 0x42600000
	v_cmp_ge_f32_e32 vcc, s2, v0
	v_mov_b32_e32 v4, 0x6600
	v_readlane_b32 s2, v255, 41
	v_mad_i32_i24 v3, s7, v4, v3
	s_lshl_b32 s2, s2, 1
	v_lshl_add_u64 v[2:3], v[2:3], 0, s[2:3]
	v_lshl_add_u64 v[2:3], v[146:147], 1, v[2:3]
	v_lshl_add_u64 v[82:83], v[2:3], 0, s[24:25]
	s_mul_i32 s25, s14, 0x6600000
	s_mul_hi_i32 s24, s14, 0x6600000
	s_add_u32 s12, s12, s25
	s_addc_u32 s13, s13, s24
	s_add_u32 s12, s12, s2
	s_addc_u32 s13, s13, 0
	s_add_u32 s12, s12, 0x1800
	s_addc_u32 s13, s13, 0
	s_ashr_i32 s17, s16, 31
	s_lshl_b64 s[14:15], s[16:17], 20
	s_add_u32 s14, s26, s14
	s_addc_u32 s15, s27, s15
	s_mul_hi_i32 s26, s8, 0x7604000
	s_mul_i32 s27, s8, 0x7604000
	s_and_saveexec_b64 s[16:17], vcc
	s_xor_b64 s[16:17], exec, s[16:17]
	s_cbranch_execz .LBB0_567
; DI int get_tid() { int t = threadIdx.x; asm volatile("" : "+v"(t)); return t; }
;     ...
;   const int tid = get_tid(), lane = tid & 63, r = lane & 31, h = lane >> 5;
;   bf16x8 qf[NQ];
; #pragma unroll
;   for (int ks = 0; ks < NQ; ++ks) qf[ks] = qpre ? qpre[ks] : *(const bf16x8*)(Qw + (size_t)r * ldq + 16 * ks + 8 * h);
;   if (zero_o) {
; #pragma unroll
;     for (int dt = 0; dt < 4; ++dt)
; #pragma unroll
;       for (int e = 0; e < 16; ++e) o[dt][e] = 0.f;
;   }
;   float m_run = -1e30f, l_run = 0.f;
;   u32x4 rk[NKL], rv[2];
;   u32 koff[NKL]; int klds[NKL];
; #pragma unroll
;   for (int i = 0; i < NKL; ++i) { int c = tid + NTHR * i; int row = c / KCH, kc = c % KCH; koff[i] = (u32)(row * ldk + 8 * kc) * 2u; klds[i] = row * KST + 8 * kc; }
;   const u32 voff = (u32)((tid >> 3) * 4096 + 8 * (tid & 7)) * 2u;
;   const int vlds = 64 * KST + (tid >> 3) * 72 + 8 * (tid & 7);
;   auto gload = [&](int k0) __attribute__((always_inline)) {
;     const char* kb = (const char*)Kg + (size_t)k0 * ldk * 2;
; #pragma unroll
;     for (int i = 0; i < NKL; ++i) rk[i] = *(const u32x4*)(kb + koff[i]);
;     const char* vb = (const char*)VTg + (size_t)k0 * 2;
; #pragma unroll
;     for (int i = 0; i < 2; ++i) rv[i] = *(const u32x4*)(vb + (size_t)i * 64 * 4096 * 2 + voff);
;   };
;   auto lstore = [&](int b) __attribute__((always_inline)) {
;     u16* St = S0 + b * STG;
; #pragma unroll
;     for (int i = 0; i < NKL; ++i) *(u32x4*)(St + klds[i]) = rk[i];
; #pragma unroll
;     for (int i = 0; i < 2; ++i) *(u32x4*)(St + vlds + i * 64 * 72) = rv[i];
;   };
;   gload(kt0 * 64);
;   __syncthreads();
;   lstore(0);
;   gload((kt0 + 1) * 64);
;   __syncthreads();
;   const float qpos = (float)(qpos0 + r);
	v_mov_b32_e32 v19, v250
	v_xor_b32_e32 v66, 0x80000000, v0
	v_ashrrev_i32_e32 v2, 31, v19
	v_lshrrev_b32_e32 v2, 28, v2
	v_add_u32_e32 v2, v19, v2
	v_ashrrev_i32_e32 v23, 4, v2
	v_and_b32_e32 v2, 0x1ffffff0, v2
	v_sub_u32_e32 v2, v19, v2
	v_mul_lo_u32 v3, v23, s56
	v_lshl_add_u32 v18, v2, 3, v3
	v_add_u32_e32 v2, 0x200, v19
	v_ashrrev_i32_e32 v3, 31, v2
	v_lshrrev_b32_e32 v3, 28, v3
	v_add_u32_e32 v3, v2, v3
	v_ashrrev_i32_e32 v32, 4, v3
	v_and_b32_e32 v3, 0x1ffffff0, v3
	v_sub_u32_e32 v2, v2, v3
	v_mul_lo_u32 v3, v32, s56
	v_lshl_add_u32 v22, v2, 3, v3
	v_ashrrev_i32_e32 v27, 3, v19
	v_lshlrev_b32_e32 v2, 3, v19
	v_and_b32_e32 v33, 31, v19
	v_and_b32_e32 v26, 56, v2
	v_lshlrev_b32_e32 v2, 13, v27
	v_lshrrev_b32_e32 v0, 2, v19
	v_mul_u32_u24_e32 v19, 0x3300, v33
	v_lshl_or_b32 v28, v26, 1, v2
	v_mov_b32_e32 v29, v1
	v_and_b32_e32 v34, 8, v0
	v_lshlrev_b32_e32 v0, 1, v19
	s_movk_i32 s71, 0x48
	v_lshl_add_u64 v[10:11], s[14:15], 0, v[28:29]
	s_mov_b32 s70, 0x80000
	s_add_u32 s74, s12, 0x198000
	v_mad_u64_u32 v[148:149], s[84:85], v27, s71, v[26:27]
	v_lshl_add_u64 v[26:27], v[82:83], 0, v[0:1]
	v_lshlrev_b32_e32 v0, 1, v34
	v_lshlrev_b32_e32 v20, 1, v18
	v_add_co_u32_e32 v30, vcc, s70, v10
	s_addc_u32 s75, s13, 0
	v_lshl_add_u64 v[26:27], v[26:27], 0, v[0:1]
	v_lshlrev_b32_e32 v24, 1, v22
	global_load_dwordx4 v[2:5], v20, s[12:13]
	global_load_dwordx4 v[6:9], v24, s[12:13]
	v_addc_co_u32_e32 v31, vcc, 0, v11, vcc
	global_load_dwordx4 v[10:13], v28, s[14:15]
	global_load_dwordx4 v[14:17], v[30:31], off
	global_load_dwordx4 v[114:117], v[26:27], off
	global_load_dwordx4 v[118:121], v[26:27], off offset:32
	global_load_dwordx4 v[122:125], v[26:27], off offset:64
	global_load_dwordx4 v[126:129], v[26:27], off offset:96
	s_barrier
	global_load_dwordx4 v[130:133], v20, s[74:75]
	global_load_dwordx4 v[134:137], v24, s[74:75]
	global_load_dwordx4 v[138:141], v28, s[14:15] offset:128
	global_load_dwordx4 v[142:145], v[30:31], off offset:128
	v_lshl_add_u32 v19, v148, 1, 64
	s_movk_i32 s71, 0xcd88
	v_mad_u64_u32 v[150:151], s[84:85], v23, s71, v[18:19]
	v_mad_u64_u32 v[152:153], s[84:85], v32, s71, v[22:23]
	v_readlane_b32 s71, v255, 25
	s_or_b32 s71, s71, s19
	s_bfe_i32 s75, s71, 0x1001a
	s_bfe_i32 s74, s71, 0x1b0000
	s_lshl_b64 s[74:75], s[74:75], 20
	s_add_u32 s74, s27, s74
	s_addc_u32 s75, s26, s75
	v_readlane_b32 s71, v255, 44
	v_mov_b32_e32 v154, v28
	v_add_u32_e32 v155, 0x80000, v28
	s_add_u32 s100, s74, s62
	s_addc_u32 s101, s75, s63
	s_add_u32 s100, s100, 0x7046000
	s_addc_u32 s101, s101, 0
	s_add_u32 s71, s71, s25
	v_readlane_b32 s74, v255, 45
	s_addc_u32 s75, s74, s24
	v_lshl_add_u32 v18, v150, 1, 64
	s_add_u32 s74, s71, s10
	v_mov_b32_e32 v21, v1
	v_mov_b32_e32 v25, v1
	v_lshl_add_u32 v22, v152, 1, 64
	s_addc_u32 s75, s75, s11
	v_mov_b32_e32 v147, 0
	s_mov_b32 s70, 0
	v_mov_b32_e32 v67, v66
	v_mov_b32_e32 v68, v66
	v_mov_b32_e32 v69, v66
	v_mov_b32_e32 v70, v66
	v_mov_b32_e32 v71, v66
	v_mov_b32_e32 v72, v66
	v_mov_b32_e32 v73, v66
	v_mov_b32_e32 v74, v66
	v_mov_b32_e32 v75, v66
	v_mov_b32_e32 v76, v66
	v_mov_b32_e32 v77, v66
	v_mov_b32_e32 v78, v66
	v_mov_b32_e32 v79, v66
	v_mov_b32_e32 v80, v66
	v_mov_b32_e32 v81, v66
	v_mul_u32_u24_e32 v149, 0x110, v33
	v_mov_b32_e32 v156, v20
	s_waitcnt vmcnt(11)
	ds_write_b128 v18, v[2:5]
	s_waitcnt vmcnt(10)
	ds_write_b128 v22, v[6:9]
	s_waitcnt vmcnt(9)
	ds_write_b128 v19, v[10:13] offset:17408
	s_waitcnt vmcnt(8)
	ds_write_b128 v19, v[14:17] offset:26624
	v_mul_u32_u24_e32 v2, 0x48, v33
	v_mov_b32_e32 v157, v24
	s_add_u32 s74, s74, s62
	s_addc_u32 s75, s75, s63
	v_lshlrev_b32_e32 v151, 1, v2
	v_mov_b32_e32 v18, 0
	v_mov_b32_e32 v19, v147
	v_mov_b32_e32 v20, v147
	v_mov_b32_e32 v21, v147
	v_mov_b32_e32 v22, v147
	v_mov_b32_e32 v23, v147
	v_mov_b32_e32 v24, v147
	v_mov_b32_e32 v25, v147
	v_mov_b32_e32 v26, v147
	v_mov_b32_e32 v27, v147
	v_mov_b32_e32 v28, v147
	v_mov_b32_e32 v29, v147
	v_mov_b32_e32 v30, v147
	v_mov_b32_e32 v31, v147
	v_mov_b32_e32 v32, v147
	v_mov_b32_e32 v33, v147
	v_mov_b32_e32 v34, 0
	v_mov_b32_e32 v35, v147
	v_mov_b32_e32 v36, v147
	v_mov_b32_e32 v37, v147
	v_mov_b32_e32 v38, v147
	v_mov_b32_e32 v39, v147
	v_mov_b32_e32 v40, v147
	v_mov_b32_e32 v41, v147
	v_mov_b32_e32 v42, v147
	v_mov_b32_e32 v43, v147
	v_mov_b32_e32 v44, v147
	v_mov_b32_e32 v45, v147
	v_mov_b32_e32 v46, v147
	v_mov_b32_e32 v47, v147
	v_mov_b32_e32 v48, v147
	v_mov_b32_e32 v49, v147
	v_mov_b32_e32 v50, 0
	v_mov_b32_e32 v51, v147
	v_mov_b32_e32 v52, v147
	v_mov_b32_e32 v53, v147
	v_mov_b32_e32 v54, v147
	v_mov_b32_e32 v55, v147
	v_mov_b32_e32 v56, v147
	v_mov_b32_e32 v57, v147
	v_mov_b32_e32 v58, v147
	v_mov_b32_e32 v59, v147
	v_mov_b32_e32 v60, v147
	v_mov_b32_e32 v61, v147
	v_mov_b32_e32 v62, v147
	v_mov_b32_e32 v63, v147
	v_mov_b32_e32 v64, v147
	v_mov_b32_e32 v65, v147
	v_mov_b32_e32 v2, 0
	v_mov_b32_e32 v3, v147
	v_mov_b32_e32 v4, v147
	v_mov_b32_e32 v5, v147
	v_mov_b32_e32 v6, v147
	v_mov_b32_e32 v7, v147
	v_mov_b32_e32 v8, v147
	v_mov_b32_e32 v9, v147
	v_mov_b32_e32 v10, v147
	v_mov_b32_e32 v11, v147
	v_mov_b32_e32 v12, v147
	v_mov_b32_e32 v13, v147
	v_mov_b32_e32 v14, v147
	v_mov_b32_e32 v15, v147
	v_mov_b32_e32 v16, v147
	v_mov_b32_e32 v17, v147
	s_waitcnt lgkmcnt(0)
	s_barrier
	v_mov_b32_e32 v170, 0
	v_mov_b32_e32 v171, 0
	v_mov_b32_e32 v172, 0
	v_mov_b32_e32 v173, 0
	v_mov_b32_e32 v174, 0
	v_mov_b32_e32 v175, 0
	v_mov_b32_e32 v176, 0
	v_mov_b32_e32 v177, 0
	v_mov_b32_e32 v178, 0
	v_mov_b32_e32 v179, 0
	v_mov_b32_e32 v180, 0
	v_mov_b32_e32 v181, 0
	v_mov_b32_e32 v182, 0
	v_mov_b32_e32 v183, 0
	v_mov_b32_e32 v184, 0
	v_mov_b32_e32 v185, 0
	v_mov_b32_e32 v246, 0
	v_mov_b32_e32 v247, 0
	v_mov_b32_e32 v248, 0
	v_mov_b32_e32 v249, 0
	v_mov_b32_e32 v82, 0
	v_mov_b32_e32 v83, 0
	v_mov_b32_e32 v84, 0
	v_mov_b32_e32 v85, 0
	v_mov_b32_e32 v86, 0
	v_mov_b32_e32 v87, 0
	v_mov_b32_e32 v88, 0
	v_mov_b32_e32 v89, 0
	v_mov_b32_e32 v90, 0
	v_mov_b32_e32 v91, 0
	v_mov_b32_e32 v92, 0
	v_mov_b32_e32 v93, 0
	v_mov_b32_e32 v94, 0
	v_mov_b32_e32 v95, 0
	v_mov_b32_e32 v96, 0
	v_mov_b32_e32 v97, 0
	v_lshlrev_b32_e32 v166, 1, v146
	v_add3_u32 v206, v149, v166, v0
	v_add_u32_e32 v206, 64, v206
	v_add_u32_e32 v207, 0x8c00, v206
	v_add3_u32 v208, 64, v0, v151
	v_add_u32_e32 v209, 0x8c00, v208
	v_lshl_add_u32 v210, v150, 1, 64
	v_add_u32_e32 v211, 0x8c00, v210
	v_lshl_add_u32 v212, v152, 1, 64
	v_add_u32_e32 v213, 0x8c00, v212
	v_lshl_add_u32 v214, v148, 1, 64
	v_add_u32_e32 v215, 0x8c00, v214
.LBB0_560:
	ds_read_b128 v[186:189], v206
	ds_read_b128 v[190:193], v206 offset:32
	ds_read_b128 v[194:197], v206 offset:64
	ds_read_b128 v[198:201], v206 offset:96
	v_mfma_f32_32x32x16_bf16 v[2:17], v[170:173], v[246:249], v[2:17]
	ds_read_b128 v[170:173], v206 offset:8704
	v_add_f32_e32 v166, v82, v83
	v_mfma_f32_32x32x16_bf16 v[50:65], v[174:177], v[246:249], v[50:65]
	ds_read_b128 v[174:177], v206 offset:8736
	s_waitcnt vmcnt(0)
	v_add_f32_e32 v166, v84, v166
	v_add_f32_e32 v166, v85, v166
	v_add_f32_e32 v166, v86, v166
	v_add_f32_e32 v166, v87, v166
	s_waitcnt lgkmcnt(5)
	v_mfma_f32_32x32x16_bf16 v[98:113], v[186:189], v[114:117], v[66:81]
	ds_read_b128 v[186:189], v208 offset:17408
	ds_write_b128 v211, v[130:133]
	ds_write_b128 v213, v[134:137]
	v_add_f32_e32 v166, v88, v166
	v_add_f32_e32 v166, v89, v166
	s_waitcnt lgkmcnt(7)
	v_mfma_f32_32x32x16_bf16 v[98:113], v[190:193], v[118:121], v[98:113]
	ds_read_b128 v[190:193], v208 offset:22016
	ds_write_b128 v215, v[138:141] offset:17408
	ds_write_b128 v215, v[142:145] offset:26624
	v_add_f32_e32 v166, v90, v166
	v_add_f32_e32 v166, v91, v166
	s_waitcnt lgkmcnt(9)
	v_mfma_f32_32x32x16_bf16 v[98:113], v[194:197], v[122:125], v[98:113]
	ds_read_b128 v[194:197], v208 offset:26624
	s_waitcnt lgkmcnt(9)
	v_mfma_f32_32x32x16_bf16 v[98:113], v[198:201], v[126:129], v[98:113]
	ds_read_b128 v[198:201], v208 offset:31232
	s_cmp_gt_u32 s70, 61
	s_cbranch_scc1 .Ldiff_skip_gb0
	global_load_dwordx4 v[130:133], v156, s[74:75]
	global_load_dwordx4 v[134:137], v157, s[74:75]
	global_load_dwordx4 v[138:141], v154, s[100:101] offset:512
	global_load_dwordx4 v[142:145], v155, s[100:101] offset:512
.Ldiff_skip_gb0:
	s_add_u32 s74, s74, s90
	s_addc_u32 s75, s75, s91
	s_add_u32 s100, s100, s30
	s_addc_u32 s101, s101, s31
	v_mfma_f32_32x32x16_bf16 v[34:49], v[178:181], v[246:249], v[34:49]
	ds_read_b128 v[178:181], v206 offset:8768
	v_add_f32_e32 v166, v92, v166
	v_add_f32_e32 v166, v93, v166
	v_mfma_f32_32x32x16_bf16 v[18:33], v[182:185], v[246:249], v[18:33]
	ds_read_b128 v[182:185], v206 offset:8800
	v_add_f32_e32 v166, v94, v166
	v_add_f32_e32 v166, v95, v166
	v_add_f32_e32 v166, v96, v166
	v_add_f32_e32 v166, v97, v166
	v_add_f32_e32 v147, v147, v166
	s_waitcnt lgkmcnt(11)
	v_mfma_f32_32x32x16_bf16 v[82:97], v[170:173], v[114:117], v[66:81]
	v_exp_f32_e32 v98, v98
	v_exp_f32_e32 v99, v99
	v_exp_f32_e32 v100, v100
	s_waitcnt lgkmcnt(10)
	v_mfma_f32_32x32x16_bf16 v[82:97], v[174:177], v[118:121], v[82:97]
	ds_read_b128 v[170:173], v208 offset:17440
	v_exp_f32_e32 v101, v101
	v_exp_f32_e32 v102, v102
	v_exp_f32_e32 v103, v103
	s_waitcnt lgkmcnt(2)
	v_mfma_f32_32x32x16_bf16 v[82:97], v[178:181], v[122:125], v[82:97]
	ds_read_b128 v[174:177], v208 offset:22048
	v_exp_f32_e32 v104, v104
	v_exp_f32_e32 v105, v105
	v_cvt_pk_bf16_f32 v202, v98, v99
	v_cvt_pk_bf16_f32 v203, v100, v101
	v_cvt_pk_bf16_f32 v204, v102, v103
	v_cvt_pk_bf16_f32 v205, v104, v105
	s_waitcnt lgkmcnt(2)
	v_mfma_f32_32x32x16_bf16 v[82:97], v[182:185], v[126:129], v[82:97]
	ds_read_b128 v[178:181], v208 offset:26656
	v_exp_f32_e32 v106, v106
	v_exp_f32_e32 v107, v107
	v_exp_f32_e32 v108, v108
	v_mfma_f32_32x32x16_bf16 v[2:17], v[186:189], v[202:205], v[2:17]
	ds_read_b128 v[182:185], v208 offset:31264
	ds_read_b128 v[186:189], v208 offset:17472
	v_exp_f32_e32 v109, v109
	v_exp_f32_e32 v110, v110
	v_exp_f32_e32 v111, v111
	v_mfma_f32_32x32x16_bf16 v[50:65], v[190:193], v[202:205], v[50:65]
	ds_read_b128 v[190:193], v208 offset:22080
	v_exp_f32_e32 v112, v112
	v_exp_f32_e32 v113, v113
	v_add_f32_e32 v160, v98, v99
	v_add_f32_e32 v160, v100, v160
	v_mfma_f32_32x32x16_bf16 v[34:49], v[194:197], v[202:205], v[34:49]
	ds_read_b128 v[194:197], v208 offset:26688
	v_cvt_pk_bf16_f32 v246, v106, v107
	v_cvt_pk_bf16_f32 v247, v108, v109
	v_cvt_pk_bf16_f32 v248, v110, v111
	v_cvt_pk_bf16_f32 v249, v112, v113
	v_add_f32_e32 v160, v101, v160
	v_add_f32_e32 v160, v102, v160
	v_mfma_f32_32x32x16_bf16 v[18:33], v[198:201], v[202:205], v[18:33]
	ds_read_b128 v[198:201], v208 offset:31296
	v_exp_f32_e32 v82, v82
	v_exp_f32_e32 v83, v83
	v_exp_f32_e32 v84, v84
	s_waitcnt lgkmcnt(7)
	v_mfma_f32_32x32x16_bf16 v[2:17], v[170:173], v[246:249], v[2:17]
	ds_read_b128 v[170:173], v208 offset:17504
	v_exp_f32_e32 v85, v85
	v_exp_f32_e32 v86, v86
	v_exp_f32_e32 v87, v87
	s_waitcnt lgkmcnt(7)
	v_mfma_f32_32x32x16_bf16 v[50:65], v[174:177], v[246:249], v[50:65]
	ds_read_b128 v[174:177], v208 offset:22112
	v_exp_f32_e32 v88, v88
	v_exp_f32_e32 v89, v89
	v_cvt_pk_bf16_f32 v202, v82, v83
	v_add_f32_e32 v160, v103, v160
	s_waitcnt lgkmcnt(7)
	v_mfma_f32_32x32x16_bf16 v[34:49], v[178:181], v[246:249], v[34:49]
	ds_read_b128 v[178:181], v208 offset:26720
	v_cvt_pk_bf16_f32 v203, v84, v85
	v_cvt_pk_bf16_f32 v204, v86, v87
	v_cvt_pk_bf16_f32 v205, v88, v89
	v_exp_f32_e32 v90, v90
	v_add_f32_e32 v160, v104, v160
	s_waitcnt lgkmcnt(7)
	v_mfma_f32_32x32x16_bf16 v[18:33], v[182:185], v[246:249], v[18:33]
	ds_read_b128 v[182:185], v208 offset:31328
	v_exp_f32_e32 v91, v91
	v_exp_f32_e32 v92, v92
	v_exp_f32_e32 v93, v93
	s_waitcnt lgkmcnt(7)
	v_mfma_f32_32x32x16_bf16 v[2:17], v[186:189], v[202:205], v[2:17]
	v_exp_f32_e32 v94, v94
	v_exp_f32_e32 v95, v95
	v_exp_f32_e32 v96, v96
	s_waitcnt lgkmcnt(6)
	v_mfma_f32_32x32x16_bf16 v[50:65], v[190:193], v[202:205], v[50:65]
	v_exp_f32_e32 v97, v97
	v_add_f32_e32 v160, v105, v160
	v_add_f32_e32 v160, v106, v160
	v_add_f32_e32 v160, v107, v160
	v_add_f32_e32 v160, v108, v160
	v_add_f32_e32 v160, v109, v160
	s_waitcnt lgkmcnt(5)
	v_mfma_f32_32x32x16_bf16 v[34:49], v[194:197], v[202:205], v[34:49]
	v_cvt_pk_bf16_f32 v246, v90, v91
	v_cvt_pk_bf16_f32 v247, v92, v93
	v_cvt_pk_bf16_f32 v248, v94, v95
	v_cvt_pk_bf16_f32 v249, v96, v97
	v_add_f32_e32 v160, v110, v160
	v_add_f32_e32 v160, v111, v160
	s_waitcnt lgkmcnt(4)
	v_mfma_f32_32x32x16_bf16 v[18:33], v[198:201], v[202:205], v[18:33]
	v_add_f32_e32 v160, v112, v160
	v_add_f32_e32 v160, v113, v160
	v_add_f32_e32 v147, v147, v160
	s_waitcnt lgkmcnt(0)
	s_barrier
;     ...
;       for (int i = 0; i < 4; ++i) kf[0][i] = *(const bf16x8*)(Ks + r * KST + kcol_off + 16 * i + 8 * h);
; #pragma unroll
;       for (int g = 0; g < NBAT; ++g) {
;         if (g + 1 < NBAT) {
;           const int t2n = (g + 1) / BPT, bn = (g + 1) % BPT;
; #pragma unroll
;           for (int i = 0; i < 4; ++i) kf[(g + 1) & 1][i] = *(const bf16x8*)(Ks + (32 * t2n + r) * KST + kcol_off + 16 * (4 * bn + i) + 8 * h);
;         }
;         __builtin_amdgcn_sched_barrier(0);
;         const int t2 = g / BPT, b = g % BPT;
; #pragma unroll
;         for (int i = 0; i < 4; ++i) st[t2] = MFMA32(kf[g & 1][i], qf[4 * b + i], st[t2]);
;         __builtin_amdgcn_sched_barrier(0);
;       }
;     ...
;       float ls = 0.f;
; #pragma unroll
;       for (int t2 = 0; t2 < 2; ++t2)
; #pragma unroll
;         for (int e = 0; e < 16; ++e) { float p = __builtin_amdgcn_exp2f(st[t2][e]); st[t2][e] = p; ls += p; }
;       l_run += ls;
;     } else {
;       float mx = st[0][0];
; #pragma unroll
;       for (int t2 = 0; t2 < 2; ++t2)
; #pragma unroll
;         for (int e = 0; e < 16; ++e) mx = fmaxf(mx, st[t2][e]);
;       mx = fmaxf(mx, shx(mx, 32));
;       float mnew = fmaxf(m_run, mx);
;       float alpha = __builtin_amdgcn_exp2f(m_run - mnew);
;       const bool changed = mnew > m_run;
;       m_run = mnew;
;       float ls = 0.f;
; #pragma unroll
;       for (int t2 = 0; t2 < 2; ++t2)
; #pragma unroll
;         for (int e = 0; e < 16; ++e) { float p = __builtin_amdgcn_exp2f(st[t2][e] - mnew); st[t2][e] = p; ls += p; }
;       l_run = l_run * alpha + ls;
;       if (__any(changed)) {
; #pragma unroll
;         for (int dt = 0; dt < 4; ++dt)
; #pragma unroll
;           for (int e = 0; e < 16; ++e) o[dt][e] *= alpha;
;       }
;     }
; #pragma unroll
;     for (int c = 0; c < 4; ++c) {
;       const int t2 = c >> 1, s2 = c & 1;
;       if (c + 1 < 4) {
; #pragma unroll
;         for (int dt = 0; dt < 4; ++dt) vf[(c + 1) & 1][dt] = *(const bf16x8*)(Vs + (32 * dt + r) * 72 + 16 * (c + 1) + 8 * h);
;       }
;       u32x4 pk;
;       pk.x = pack2(st[t2][8 * s2], st[t2][8 * s2 + 1]); pk.y = pack2(st[t2][8 * s2 + 2], st[t2][8 * s2 + 3]);
;       pk.z = pack2(st[t2][8 * s2 + 4], st[t2][8 * s2 + 5]); pk.w = pack2(st[t2][8 * s2 + 6], st[t2][8 * s2 + 7]);
;       bf16x8 pf = __builtin_bit_cast(bf16x8, pk);
;       __builtin_amdgcn_sched_barrier(0);
; #pragma unroll
	ds_read_b128 v[186:189], v207
	ds_read_b128 v[190:193], v207 offset:32
	ds_read_b128 v[194:197], v207 offset:64
	ds_read_b128 v[198:201], v207 offset:96
	v_mfma_f32_32x32x16_bf16 v[2:17], v[170:173], v[246:249], v[2:17]
	ds_read_b128 v[170:173], v207 offset:8704
	v_add_f32_e32 v166, v82, v83
	v_mfma_f32_32x32x16_bf16 v[50:65], v[174:177], v[246:249], v[50:65]
	ds_read_b128 v[174:177], v207 offset:8736
	s_waitcnt vmcnt(0)
	v_add_f32_e32 v166, v84, v166
	v_add_f32_e32 v166, v85, v166
	v_add_f32_e32 v166, v86, v166
	v_add_f32_e32 v166, v87, v166
	s_waitcnt lgkmcnt(5)
	v_mfma_f32_32x32x16_bf16 v[98:113], v[186:189], v[114:117], v[66:81]
	ds_read_b128 v[186:189], v209 offset:17408
	ds_write_b128 v210, v[130:133]
	ds_write_b128 v212, v[134:137]
	v_add_f32_e32 v166, v88, v166
	v_add_f32_e32 v166, v89, v166
	s_waitcnt lgkmcnt(7)
	v_mfma_f32_32x32x16_bf16 v[98:113], v[190:193], v[118:121], v[98:113]
	ds_read_b128 v[190:193], v209 offset:22016
	ds_write_b128 v214, v[138:141] offset:17408
	ds_write_b128 v214, v[142:145] offset:26624
	v_add_f32_e32 v166, v90, v166
	v_add_f32_e32 v166, v91, v166
	s_waitcnt lgkmcnt(9)
	v_mfma_f32_32x32x16_bf16 v[98:113], v[194:197], v[122:125], v[98:113]
	ds_read_b128 v[194:197], v209 offset:26624
	s_waitcnt lgkmcnt(9)
	v_mfma_f32_32x32x16_bf16 v[98:113], v[198:201], v[126:129], v[98:113]
	ds_read_b128 v[198:201], v209 offset:31232
	s_cmp_gt_u32 s70, 61
	s_cbranch_scc1 .Ldiff_skip_gb1
	global_load_dwordx4 v[130:133], v156, s[74:75]
	global_load_dwordx4 v[134:137], v157, s[74:75]
	global_load_dwordx4 v[138:141], v154, s[100:101] offset:512
	global_load_dwordx4 v[142:145], v155, s[100:101] offset:512
.Ldiff_skip_gb1:
	s_add_u32 s74, s74, s90
	s_addc_u32 s75, s75, s91
	s_add_u32 s100, s100, s30
	s_addc_u32 s101, s101, s31
	v_mfma_f32_32x32x16_bf16 v[34:49], v[178:181], v[246:249], v[34:49]
	ds_read_b128 v[178:181], v207 offset:8768
	v_add_f32_e32 v166, v92, v166
	v_add_f32_e32 v166, v93, v166
	v_mfma_f32_32x32x16_bf16 v[18:33], v[182:185], v[246:249], v[18:33]
	ds_read_b128 v[182:185], v207 offset:8800
	v_add_f32_e32 v166, v94, v166
	v_add_f32_e32 v166, v95, v166
	v_add_f32_e32 v166, v96, v166
	v_add_f32_e32 v166, v97, v166
	v_add_f32_e32 v147, v147, v166
	s_waitcnt lgkmcnt(11)
	v_mfma_f32_32x32x16_bf16 v[82:97], v[170:173], v[114:117], v[66:81]
	v_exp_f32_e32 v98, v98
	v_exp_f32_e32 v99, v99
	v_exp_f32_e32 v100, v100
	s_waitcnt lgkmcnt(10)
	v_mfma_f32_32x32x16_bf16 v[82:97], v[174:177], v[118:121], v[82:97]
	ds_read_b128 v[170:173], v209 offset:17440
	v_exp_f32_e32 v101, v101
	v_exp_f32_e32 v102, v102
	v_exp_f32_e32 v103, v103
	s_waitcnt lgkmcnt(2)
	v_mfma_f32_32x32x16_bf16 v[82:97], v[178:181], v[122:125], v[82:97]
	ds_read_b128 v[174:177], v209 offset:22048
	v_exp_f32_e32 v104, v104
	v_exp_f32_e32 v105, v105
	v_cvt_pk_bf16_f32 v202, v98, v99
	v_cvt_pk_bf16_f32 v203, v100, v101
	v_cvt_pk_bf16_f32 v204, v102, v103
	v_cvt_pk_bf16_f32 v205, v104, v105
	s_waitcnt lgkmcnt(2)
	v_mfma_f32_32x32x16_bf16 v[82:97], v[182:185], v[126:129], v[82:97]
	ds_read_b128 v[178:181], v209 offset:26656
	v_exp_f32_e32 v106, v106
	v_exp_f32_e32 v107, v107
	v_exp_f32_e32 v108, v108
	v_mfma_f32_32x32x16_bf16 v[2:17], v[186:189], v[202:205], v[2:17]
	ds_read_b128 v[182:185], v209 offset:31264
	ds_read_b128 v[186:189], v209 offset:17472
	v_exp_f32_e32 v109, v109
	v_exp_f32_e32 v110, v110
	v_exp_f32_e32 v111, v111
	v_mfma_f32_32x32x16_bf16 v[50:65], v[190:193], v[202:205], v[50:65]
	ds_read_b128 v[190:193], v209 offset:22080
	v_exp_f32_e32 v112, v112
	v_exp_f32_e32 v113, v113
	v_add_f32_e32 v160, v98, v99
	v_add_f32_e32 v160, v100, v160
	v_mfma_f32_32x32x16_bf16 v[34:49], v[194:197], v[202:205], v[34:49]
	ds_read_b128 v[194:197], v209 offset:26688
	v_cvt_pk_bf16_f32 v246, v106, v107
	v_cvt_pk_bf16_f32 v247, v108, v109
	v_cvt_pk_bf16_f32 v248, v110, v111
	v_cvt_pk_bf16_f32 v249, v112, v113
	v_add_f32_e32 v160, v101, v160
	v_add_f32_e32 v160, v102, v160
	v_mfma_f32_32x32x16_bf16 v[18:33], v[198:201], v[202:205], v[18:33]
	ds_read_b128 v[198:201], v209 offset:31296
	v_exp_f32_e32 v82, v82
	v_exp_f32_e32 v83, v83
	v_exp_f32_e32 v84, v84
	s_waitcnt lgkmcnt(7)
	v_mfma_f32_32x32x16_bf16 v[2:17], v[170:173], v[246:249], v[2:17]
	ds_read_b128 v[170:173], v209 offset:17504
	v_exp_f32_e32 v85, v85
	v_exp_f32_e32 v86, v86
	v_exp_f32_e32 v87, v87
	s_waitcnt lgkmcnt(7)
	v_mfma_f32_32x32x16_bf16 v[50:65], v[174:177], v[246:249], v[50:65]
	ds_read_b128 v[174:177], v209 offset:22112
	v_exp_f32_e32 v88, v88
	v_exp_f32_e32 v89, v89
	v_cvt_pk_bf16_f32 v202, v82, v83
	v_add_f32_e32 v160, v103, v160
	s_waitcnt lgkmcnt(7)
	v_mfma_f32_32x32x16_bf16 v[34:49], v[178:181], v[246:249], v[34:49]
	ds_read_b128 v[178:181], v209 offset:26720
	v_cvt_pk_bf16_f32 v203, v84, v85
	v_cvt_pk_bf16_f32 v204, v86, v87
	v_cvt_pk_bf16_f32 v205, v88, v89
	v_exp_f32_e32 v90, v90
	v_add_f32_e32 v160, v104, v160
	s_waitcnt lgkmcnt(7)
	v_mfma_f32_32x32x16_bf16 v[18:33], v[182:185], v[246:249], v[18:33]
	ds_read_b128 v[182:185], v209 offset:31328
	v_exp_f32_e32 v91, v91
	v_exp_f32_e32 v92, v92
	v_exp_f32_e32 v93, v93
	s_waitcnt lgkmcnt(7)
	v_mfma_f32_32x32x16_bf16 v[2:17], v[186:189], v[202:205], v[2:17]
	v_exp_f32_e32 v94, v94
	v_exp_f32_e32 v95, v95
	v_exp_f32_e32 v96, v96
	s_waitcnt lgkmcnt(6)
	v_mfma_f32_32x32x16_bf16 v[50:65], v[190:193], v[202:205], v[50:65]
	v_exp_f32_e32 v97, v97
	v_add_f32_e32 v160, v105, v160
	v_add_f32_e32 v160, v106, v160
	v_add_f32_e32 v160, v107, v160
	v_add_f32_e32 v160, v108, v160
	v_add_f32_e32 v160, v109, v160
	s_waitcnt lgkmcnt(5)
	v_mfma_f32_32x32x16_bf16 v[34:49], v[194:197], v[202:205], v[34:49]
	v_cvt_pk_bf16_f32 v246, v90, v91
	v_cvt_pk_bf16_f32 v247, v92, v93
	v_cvt_pk_bf16_f32 v248, v94, v95
	v_cvt_pk_bf16_f32 v249, v96, v97
	v_add_f32_e32 v160, v110, v160
	v_add_f32_e32 v160, v111, v160
	s_waitcnt lgkmcnt(4)
	v_mfma_f32_32x32x16_bf16 v[18:33], v[198:201], v[202:205], v[18:33]
	v_add_f32_e32 v160, v112, v160
	v_add_f32_e32 v160, v113, v160
	v_add_f32_e32 v147, v147, v160
	s_add_i32 s70, s70, 2
	s_cmp_lg_u32 s70, 64
	s_waitcnt lgkmcnt(0)
	s_barrier
	s_cbranch_scc1 .LBB0_560
